# phase 13: odd workgroups run convert_weights before row_phase2, even after (bandwidth/latency interleave), on top of non-scaled MFMA
# speedup vs baseline: 1.0007x; 1.0007x over previous
.LBB0_1463:
	s_or_b64 exec, exec, s[0:1]
	s_mov_b32 s0, 0
	s_waitcnt lgkmcnt(0)
	s_barrier
	v_readlane_b32 s13, v252, 2
	s_mov_b32 s98, 0
	s_bitcmp1_b32 s13, 0
	s_cbranch_scc0 .Lret_c13
	s_mov_b32 s98, 1
	s_mov_b32 s12, s87
	s_mov_b32 s13, s88
	s_mov_b32 s22, 0
	s_mov_b32 s99, 0
	s_mov_b32 s100, 0xb03f
	s_mov_b32 s101, 6
	v_mov_b32_e32 v1, v0
	s_branch .Lconv1_entry
.Lret_c13:
	s_mov_b32 s0, 0
	v_mov_b32_e32 v1, v0
	s_mov_b32 s0, s87
	s_mov_b32 s0, s88
	s_mov_b32 s8, 0
	s_add_i32 s0, s8, 0x202b8
	v_mov_b32_e32 v2, v0
	s_mov_b32 s9, s87
	s_mov_b32 s23, s88
	v_mov_b32_e32 v1, s0
	ds_read_b32 v1, v1
	s_add_i32 s0, s8, 0x202bc
	v_mov_b32_e32 v3, s0
	s_add_i32 s0, s8, 0x202b0
	v_mov_b32_e32 v4, s0
	s_add_i32 s0, s8, 0x202b4
	v_mov_b32_e32 v5, s0
	s_add_i32 s0, s8, 0x20200
	s_waitcnt lgkmcnt(0)
	v_readfirstlane_b32 s2, v1
	v_mov_b32_e32 v1, s0
	ds_read_b32 v3, v3
	ds_read_b32 v4, v4
	ds_read_b32 v5, v5
	ds_read_b32 v1, v1
	s_add_i32 s0, s8, 0x20204
	s_waitcnt lgkmcnt(0)
	v_mov_b32_e32 v1, s0
	ds_read_b32 v1, v1
	s_add_i32 s0, s8, 0x20210
	s_waitcnt lgkmcnt(0)
	v_mov_b32_e32 v1, s0
	ds_read_b32 v1, v1
	s_add_i32 s0, s8, 0x20214
	s_waitcnt lgkmcnt(0)
	v_mov_b32_e32 v1, s0
	ds_read_b32 v1, v1
	s_add_i32 s0, s8, 0x202a0
	s_waitcnt lgkmcnt(0)
	v_mov_b32_e32 v1, s0
	s_add_i32 s0, s8, 0x202a4
	v_readfirstlane_b32 s3, v3
	v_mov_b32_e32 v3, s0
	s_add_i32 s0, s8, 0x202a8
	v_readfirstlane_b32 s4, v4
	v_mov_b32_e32 v4, s0
	s_add_i32 s0, s8, 0x202ac
	v_readfirstlane_b32 s5, v5
	v_mov_b32_e32 v5, s0
	ds_read_b32 v1, v1
	ds_read_b32 v3, v3
	ds_read_b32 v4, v4
	ds_read_b32 v5, v5
	s_mov_b32 s22, 0
	v_readfirstlane_b32 s10, v2
	s_waitcnt lgkmcnt(3)
	v_readfirstlane_b32 s6, v1
	s_waitcnt lgkmcnt(2)
	v_readfirstlane_b32 s7, v3
	s_waitcnt lgkmcnt(1)
	v_readfirstlane_b32 s0, v4
	s_cmpk_gt_i32 s23, 0xff
	s_waitcnt lgkmcnt(0)
	v_readfirstlane_b32 s1, v5
	s_cbranch_scc1 .LBB0_1492
	v_and_b32_e32 v130, 63, v2
	v_ashrrev_i32_e32 v3, 31, v2
	v_lshlrev_b64 v[132:133], 4, v[2:3]
	v_mov_b32_e32 v139, 0
	v_lshlrev_b32_e32 v138, 3, v130
	v_lshl_add_u32 v1, v2, 4, s8
	v_lshl_add_u64 v[136:137], s[0:1], 0, v[132:133]
	v_lshl_add_u64 v[2:3], s[2:3], 0, v[138:139]
	s_mov_b64 s[0:1], 0xe600000
	v_lshl_add_u64 v[140:141], v[2:3], 0, s[0:1]
	v_mbcnt_hi_u32_b32 v3, -1, v230
	v_and_b32_e32 v5, 64, v3
	v_add_u32_e32 v5, 64, v5
	v_xor_b32_e32 v7, 1, v3
	v_cmp_lt_i32_e32 vcc, v7, v5
	s_ashr_i32 s24, s10, 6
	s_add_u32 s25, s2, 0x100000
	v_cndmask_b32_e32 v7, v3, v7, vcc
	v_lshlrev_b32_e32 v174, 2, v7
	v_xor_b32_e32 v7, 2, v3
	v_cmp_lt_i32_e32 vcc, v7, v5
	s_addc_u32 s26, s3, 0
	v_lshl_add_u64 v[134:135], s[6:7], 0, v[132:133]
	v_cndmask_b32_e32 v7, v3, v7, vcc
	v_lshlrev_b32_e32 v175, 2, v7
	v_xor_b32_e32 v7, 4, v3
	v_cmp_lt_i32_e32 vcc, v7, v5
	s_add_u32 s6, s2, 0x1000000
	s_mul_i32 s0, s23, 0x48
	v_cndmask_b32_e32 v7, v3, v7, vcc
	v_lshlrev_b32_e32 v176, 2, v7
	v_xor_b32_e32 v7, 8, v3
	v_cmp_lt_i32_e32 vcc, v7, v5
	s_addc_u32 s7, s3, 0
	v_or_b32_e32 v2, 64, v130
	v_cndmask_b32_e32 v7, v3, v7, vcc
	v_lshlrev_b32_e32 v177, 2, v7
	v_xor_b32_e32 v7, 16, v3
	v_cmp_lt_i32_e32 vcc, v7, v5
	v_or_b32_e32 v4, 0x80, v130
	v_or_b32_e32 v6, 0xc0, v130
	v_cndmask_b32_e32 v7, v3, v7, vcc
	v_lshlrev_b32_e32 v178, 2, v7
	v_xor_b32_e32 v7, 32, v3
	v_cmp_lt_i32_e32 vcc, v7, v5
	v_or_b32_e32 v8, 0x100, v130
	v_or_b32_e32 v10, 0x140, v130
	v_or_b32_e32 v12, 0x180, v130
	v_or_b32_e32 v14, 0x1c0, v130
	v_cndmask_b32_e32 v3, v3, v7, vcc
	s_add_i32 s0, s24, s0
	v_lshl_add_u32 v131, v130, 4, s8
	v_lshlrev_b32_e32 v179, 2, v3
	s_add_i32 s27, s0, 16
	s_mul_i32 s28, s9, 0x48
	s_mov_b32 s29, 0xa000
	s_mov_b32 s30, 0x6c000
	s_mov_b32 s31, 0x6e000
	s_movk_i32 s33, 0x1000
	s_mov_b32 s8, 0x3fb504f3
	v_mov_b32_e32 v180, 0x3727c5ac
	s_mov_b32 s34, 0xf800000
	v_mov_b32_e32 v181, 0x260
	v_mov_b32_e32 v182, 0x358637bd
	v_lshlrev_b32_e32 v183, 2, v2
	v_lshlrev_b32_e32 v184, 2, v4
	v_lshlrev_b32_e32 v185, 2, v6
	v_lshlrev_b32_e32 v186, 2, v8
	v_lshlrev_b32_e32 v187, 2, v10
	v_lshlrev_b32_e32 v188, 2, v12
	v_lshlrev_b32_e32 v189, 2, v14
	v_lshlrev_b32_e32 v138, 4, v130
	s_branch .LBB0_1466

.LBB0_1492:
	v_mov_b32_e32 v1, v0
	s_barrier
	s_mov_b32 s12, s87
	s_mov_b32 s13, s88
	s_mov_b32 s99, 0
	s_cmp_eq_u32 s98, 0
	s_cbranch_scc1 .Lc13_n
	s_mov_b32 s99, 0xb040
.Lc13_n:
	s_mov_b32 s100, 0xb03f
	s_mov_b32 s101, 0

.LBB0_1515:
	s_cmp_eq_u32 s101, 6
	s_cbranch_scc1 .Lret_c13
	v_lshl_add_u32 v1, s13, 9, v1
	s_movk_i32 s2, 0x6000
	v_cmp_gt_i32_e32 vcc, s2, v1
	s_and_saveexec_b64 s[2:3], vcc
	s_cbranch_execz .LBB0_1518
	s_add_u32 s0, s0, 0x3500000
	v_mov_b32_e32 v2, 0
	s_addc_u32 s1, s1, 0
	s_lshl_b32 s6, s12, 9
	s_mov_b64 s[4:5], 0
	v_mov_b32_e32 v3, v2
	v_mov_b32_e32 v4, v2
	v_mov_b32_e32 v5, v2
	s_movk_i32 s7, 0x5fff
